# v043 + hand-written P0 adaLN K-loop: W rows double-buffered across trips, LDS activations double-buffered per row, fully unrolled
# speedup vs baseline: 1.0083x; 1.0011x over previous
.LBB0_26:
	s_mov_b64 s[34:35], 0x3000
	v_mov_b64_e32 v[18:19], v[8:9]
	global_load_dword v26, v[18:19], off
	v_lshl_add_u64 v[18:19], v[18:19], 0, s[34:35]
	global_load_dword v27, v[18:19], off
	v_lshl_add_u64 v[18:19], v[18:19], 0, s[34:35]
	global_load_dword v28, v[18:19], off
	v_lshl_add_u64 v[18:19], v[18:19], 0, s[34:35]
	global_load_dword v29, v[18:19], off
	v_lshl_add_u64 v[18:19], v[18:19], 0, s[34:35]
	global_load_dword v30, v[18:19], off
	v_lshl_add_u64 v[18:19], v[18:19], 0, s[34:35]
	global_load_dword v31, v[18:19], off
	v_lshl_add_u64 v[18:19], v[18:19], 0, s[34:35]
	global_load_dword v32, v[18:19], off
	v_lshl_add_u64 v[18:19], v[18:19], 0, s[34:35]
	global_load_dword v33, v[18:19], off
	v_lshl_add_u64 v[18:19], v[18:19], 0, s[34:35]
	global_load_dword v34, v[18:19], off
	v_lshl_add_u64 v[18:19], v[18:19], 0, s[34:35]
	global_load_dword v35, v[18:19], off
	v_lshl_add_u64 v[18:19], v[18:19], 0, s[34:35]
	global_load_dword v36, v[18:19], off
	v_lshl_add_u64 v[18:19], v[18:19], 0, s[34:35]
	global_load_dword v37, v[18:19], off
	v_lshl_add_u64 v[18:19], v[18:19], 0, s[34:35]
	global_load_dword v38, v[18:19], off
	v_lshl_add_u64 v[18:19], v[18:19], 0, s[34:35]
	global_load_dword v39, v[18:19], off
	v_lshl_add_u64 v[18:19], v[18:19], 0, s[34:35]
	global_load_dword v40, v[18:19], off
	v_lshl_add_u64 v[18:19], v[18:19], 0, s[34:35]
	global_load_dword v41, v[18:19], off
	v_lshl_add_u64 v[18:19], v[18:19], 0, s[34:35]
	v_mov_b32_e32 v20, s33
	s_add_i32 s33, s33, 64
	ds_read_b128 v[58:61], v20 offset:0
	ds_read_b128 v[62:65], v20 offset:16
	ds_read_b128 v[66:69], v20 offset:32
	ds_read_b128 v[70:73], v20 offset:48
	global_load_dword v42, v[18:19], off
	v_lshl_add_u64 v[18:19], v[18:19], 0, s[34:35]
	global_load_dword v43, v[18:19], off
	v_lshl_add_u64 v[18:19], v[18:19], 0, s[34:35]
	global_load_dword v44, v[18:19], off
	v_lshl_add_u64 v[18:19], v[18:19], 0, s[34:35]
	global_load_dword v45, v[18:19], off
	v_lshl_add_u64 v[18:19], v[18:19], 0, s[34:35]
	global_load_dword v46, v[18:19], off
	v_lshl_add_u64 v[18:19], v[18:19], 0, s[34:35]
	global_load_dword v47, v[18:19], off
	v_lshl_add_u64 v[18:19], v[18:19], 0, s[34:35]
	global_load_dword v48, v[18:19], off
	v_lshl_add_u64 v[18:19], v[18:19], 0, s[34:35]
	global_load_dword v49, v[18:19], off
	v_lshl_add_u64 v[18:19], v[18:19], 0, s[34:35]
	global_load_dword v50, v[18:19], off
	v_lshl_add_u64 v[18:19], v[18:19], 0, s[34:35]
	global_load_dword v51, v[18:19], off
	v_lshl_add_u64 v[18:19], v[18:19], 0, s[34:35]
	global_load_dword v52, v[18:19], off
	v_lshl_add_u64 v[18:19], v[18:19], 0, s[34:35]
	global_load_dword v53, v[18:19], off
	v_lshl_add_u64 v[18:19], v[18:19], 0, s[34:35]
	global_load_dword v54, v[18:19], off
	v_lshl_add_u64 v[18:19], v[18:19], 0, s[34:35]
	global_load_dword v55, v[18:19], off
	v_lshl_add_u64 v[18:19], v[18:19], 0, s[34:35]
	global_load_dword v56, v[18:19], off
	v_lshl_add_u64 v[18:19], v[18:19], 0, s[34:35]
	global_load_dword v57, v[18:19], off
	v_lshl_add_u64 v[18:19], v[18:19], 0, s[34:35]
	s_waitcnt vmcnt(16)
	ds_read_b128 v[74:77], v20 offset:4096
	ds_read_b128 v[78:81], v20 offset:4112
	ds_read_b128 v[82:85], v20 offset:4128
	ds_read_b128 v[86:89], v20 offset:4144
	s_waitcnt lgkmcnt(4)
	v_fmac_f32_e32 v12, v58, v26
	v_fmac_f32_e32 v12, v59, v27
	v_fmac_f32_e32 v12, v60, v28
	v_fmac_f32_e32 v12, v61, v29
	v_fmac_f32_e32 v12, v62, v30
	v_fmac_f32_e32 v12, v63, v31
	v_fmac_f32_e32 v12, v64, v32
	v_fmac_f32_e32 v12, v65, v33
	v_fmac_f32_e32 v12, v66, v34
	v_fmac_f32_e32 v12, v67, v35
	v_fmac_f32_e32 v12, v68, v36
	v_fmac_f32_e32 v12, v69, v37
	v_fmac_f32_e32 v12, v70, v38
	v_fmac_f32_e32 v12, v71, v39
	v_fmac_f32_e32 v12, v72, v40
	v_fmac_f32_e32 v12, v73, v41
	ds_read_b128 v[58:61], v20 offset:8192
	ds_read_b128 v[62:65], v20 offset:8208
	ds_read_b128 v[66:69], v20 offset:8224
	ds_read_b128 v[70:73], v20 offset:8240
	s_waitcnt lgkmcnt(4)
	v_fmac_f32_e32 v13, v74, v26
	v_fmac_f32_e32 v13, v75, v27
	v_fmac_f32_e32 v13, v76, v28
	v_fmac_f32_e32 v13, v77, v29
	v_fmac_f32_e32 v13, v78, v30
	v_fmac_f32_e32 v13, v79, v31
	v_fmac_f32_e32 v13, v80, v32
	v_fmac_f32_e32 v13, v81, v33
	v_fmac_f32_e32 v13, v82, v34
	v_fmac_f32_e32 v13, v83, v35
	v_fmac_f32_e32 v13, v84, v36
	v_fmac_f32_e32 v13, v85, v37
	v_fmac_f32_e32 v13, v86, v38
	v_fmac_f32_e32 v13, v87, v39
	v_fmac_f32_e32 v13, v88, v40
	v_fmac_f32_e32 v13, v89, v41
	ds_read_b128 v[74:77], v20 offset:12288
	ds_read_b128 v[78:81], v20 offset:12304
	ds_read_b128 v[82:85], v20 offset:12320
	ds_read_b128 v[86:89], v20 offset:12336
	s_waitcnt lgkmcnt(4)
	v_fmac_f32_e32 v14, v58, v26
	v_fmac_f32_e32 v14, v59, v27
	v_fmac_f32_e32 v14, v60, v28
	v_fmac_f32_e32 v14, v61, v29
	v_fmac_f32_e32 v14, v62, v30
	v_fmac_f32_e32 v14, v63, v31
	v_fmac_f32_e32 v14, v64, v32
	v_fmac_f32_e32 v14, v65, v33
	v_fmac_f32_e32 v14, v66, v34
	v_fmac_f32_e32 v14, v67, v35
	v_fmac_f32_e32 v14, v68, v36
	v_fmac_f32_e32 v14, v69, v37
	v_fmac_f32_e32 v14, v70, v38
	v_fmac_f32_e32 v14, v71, v39
	v_fmac_f32_e32 v14, v72, v40
	v_fmac_f32_e32 v14, v73, v41
	ds_read_b128 v[58:61], v20 offset:16384
	ds_read_b128 v[62:65], v20 offset:16400
	ds_read_b128 v[66:69], v20 offset:16416
	ds_read_b128 v[70:73], v20 offset:16432
	s_waitcnt lgkmcnt(4)
	v_fmac_f32_e32 v15, v74, v26
	v_fmac_f32_e32 v15, v75, v27
	v_fmac_f32_e32 v15, v76, v28
	v_fmac_f32_e32 v15, v77, v29
	v_fmac_f32_e32 v15, v78, v30
	v_fmac_f32_e32 v15, v79, v31
	v_fmac_f32_e32 v15, v80, v32
	v_fmac_f32_e32 v15, v81, v33
	v_fmac_f32_e32 v15, v82, v34
	v_fmac_f32_e32 v15, v83, v35
	v_fmac_f32_e32 v15, v84, v36
	v_fmac_f32_e32 v15, v85, v37
	v_fmac_f32_e32 v15, v86, v38
	v_fmac_f32_e32 v15, v87, v39
	v_fmac_f32_e32 v15, v88, v40
	v_fmac_f32_e32 v15, v89, v41
	ds_read_b128 v[74:77], v20 offset:20480
	ds_read_b128 v[78:81], v20 offset:20496
	ds_read_b128 v[82:85], v20 offset:20512
	ds_read_b128 v[86:89], v20 offset:20528
	s_waitcnt lgkmcnt(4)
	v_fmac_f32_e32 v16, v58, v26
	v_fmac_f32_e32 v16, v59, v27
	v_fmac_f32_e32 v16, v60, v28
	v_fmac_f32_e32 v16, v61, v29
	v_fmac_f32_e32 v16, v62, v30
	v_fmac_f32_e32 v16, v63, v31
	v_fmac_f32_e32 v16, v64, v32
	v_fmac_f32_e32 v16, v65, v33
	v_fmac_f32_e32 v16, v66, v34
	v_fmac_f32_e32 v16, v67, v35
	v_fmac_f32_e32 v16, v68, v36
	v_fmac_f32_e32 v16, v69, v37
	v_fmac_f32_e32 v16, v70, v38
	v_fmac_f32_e32 v16, v71, v39
	v_fmac_f32_e32 v16, v72, v40
	v_fmac_f32_e32 v16, v73, v41
	ds_read_b128 v[58:61], v20 offset:24576
	ds_read_b128 v[62:65], v20 offset:24592
	ds_read_b128 v[66:69], v20 offset:24608
	ds_read_b128 v[70:73], v20 offset:24624
	s_waitcnt lgkmcnt(4)
	v_fmac_f32_e32 v17, v74, v26
	v_fmac_f32_e32 v17, v75, v27
	v_fmac_f32_e32 v17, v76, v28
	v_fmac_f32_e32 v17, v77, v29
	v_fmac_f32_e32 v17, v78, v30
	v_fmac_f32_e32 v17, v79, v31
	v_fmac_f32_e32 v17, v80, v32
	v_fmac_f32_e32 v17, v81, v33
	v_fmac_f32_e32 v17, v82, v34
	v_fmac_f32_e32 v17, v83, v35
	v_fmac_f32_e32 v17, v84, v36
	v_fmac_f32_e32 v17, v85, v37
	v_fmac_f32_e32 v17, v86, v38
	v_fmac_f32_e32 v17, v87, v39
	v_fmac_f32_e32 v17, v88, v40
	v_fmac_f32_e32 v17, v89, v41
	ds_read_b128 v[74:77], v20 offset:28672
	ds_read_b128 v[78:81], v20 offset:28688
	ds_read_b128 v[82:85], v20 offset:28704
	ds_read_b128 v[86:89], v20 offset:28720
	s_waitcnt lgkmcnt(4)
	v_fmac_f32_e32 v10, v58, v26
	v_fmac_f32_e32 v10, v59, v27
	v_fmac_f32_e32 v10, v60, v28
	v_fmac_f32_e32 v10, v61, v29
	v_fmac_f32_e32 v10, v62, v30
	v_fmac_f32_e32 v10, v63, v31
	v_fmac_f32_e32 v10, v64, v32
	v_fmac_f32_e32 v10, v65, v33
	v_fmac_f32_e32 v10, v66, v34
	v_fmac_f32_e32 v10, v67, v35
	v_fmac_f32_e32 v10, v68, v36
	v_fmac_f32_e32 v10, v69, v37
	v_fmac_f32_e32 v10, v70, v38
	v_fmac_f32_e32 v10, v71, v39
	v_fmac_f32_e32 v10, v72, v40
	v_fmac_f32_e32 v10, v73, v41
	s_waitcnt lgkmcnt(0)
	v_fmac_f32_e32 v11, v74, v26
	v_fmac_f32_e32 v11, v75, v27
	v_fmac_f32_e32 v11, v76, v28
	v_fmac_f32_e32 v11, v77, v29
	v_fmac_f32_e32 v11, v78, v30
	v_fmac_f32_e32 v11, v79, v31
	v_fmac_f32_e32 v11, v80, v32
	v_fmac_f32_e32 v11, v81, v33
	v_fmac_f32_e32 v11, v82, v34
	v_fmac_f32_e32 v11, v83, v35
	v_fmac_f32_e32 v11, v84, v36
	v_fmac_f32_e32 v11, v85, v37
	v_fmac_f32_e32 v11, v86, v38
	v_fmac_f32_e32 v11, v87, v39
	v_fmac_f32_e32 v11, v88, v40
	v_fmac_f32_e32 v11, v89, v41
	v_mov_b32_e32 v20, s33
	s_add_i32 s33, s33, 64
	ds_read_b128 v[58:61], v20 offset:0
	ds_read_b128 v[62:65], v20 offset:16
	ds_read_b128 v[66:69], v20 offset:32
	ds_read_b128 v[70:73], v20 offset:48
	global_load_dword v26, v[18:19], off
	v_lshl_add_u64 v[18:19], v[18:19], 0, s[34:35]
	global_load_dword v27, v[18:19], off
	v_lshl_add_u64 v[18:19], v[18:19], 0, s[34:35]
	global_load_dword v28, v[18:19], off
	v_lshl_add_u64 v[18:19], v[18:19], 0, s[34:35]
	global_load_dword v29, v[18:19], off
	v_lshl_add_u64 v[18:19], v[18:19], 0, s[34:35]
	global_load_dword v30, v[18:19], off
	v_lshl_add_u64 v[18:19], v[18:19], 0, s[34:35]
	global_load_dword v31, v[18:19], off
	v_lshl_add_u64 v[18:19], v[18:19], 0, s[34:35]
	global_load_dword v32, v[18:19], off
	v_lshl_add_u64 v[18:19], v[18:19], 0, s[34:35]
	global_load_dword v33, v[18:19], off
	v_lshl_add_u64 v[18:19], v[18:19], 0, s[34:35]
	global_load_dword v34, v[18:19], off
	v_lshl_add_u64 v[18:19], v[18:19], 0, s[34:35]
	global_load_dword v35, v[18:19], off
	v_lshl_add_u64 v[18:19], v[18:19], 0, s[34:35]
	global_load_dword v36, v[18:19], off
	v_lshl_add_u64 v[18:19], v[18:19], 0, s[34:35]
	global_load_dword v37, v[18:19], off
	v_lshl_add_u64 v[18:19], v[18:19], 0, s[34:35]
	global_load_dword v38, v[18:19], off
	v_lshl_add_u64 v[18:19], v[18:19], 0, s[34:35]
	global_load_dword v39, v[18:19], off
	v_lshl_add_u64 v[18:19], v[18:19], 0, s[34:35]
	global_load_dword v40, v[18:19], off
	v_lshl_add_u64 v[18:19], v[18:19], 0, s[34:35]
	global_load_dword v41, v[18:19], off
	v_lshl_add_u64 v[18:19], v[18:19], 0, s[34:35]
	s_waitcnt vmcnt(16)
	ds_read_b128 v[74:77], v20 offset:4096
	ds_read_b128 v[78:81], v20 offset:4112
	ds_read_b128 v[82:85], v20 offset:4128
	ds_read_b128 v[86:89], v20 offset:4144
	s_waitcnt lgkmcnt(4)
	v_fmac_f32_e32 v12, v58, v42
	v_fmac_f32_e32 v12, v59, v43
	v_fmac_f32_e32 v12, v60, v44
	v_fmac_f32_e32 v12, v61, v45
	v_fmac_f32_e32 v12, v62, v46
	v_fmac_f32_e32 v12, v63, v47
	v_fmac_f32_e32 v12, v64, v48
	v_fmac_f32_e32 v12, v65, v49
	v_fmac_f32_e32 v12, v66, v50
	v_fmac_f32_e32 v12, v67, v51
	v_fmac_f32_e32 v12, v68, v52
	v_fmac_f32_e32 v12, v69, v53
	v_fmac_f32_e32 v12, v70, v54
	v_fmac_f32_e32 v12, v71, v55
	v_fmac_f32_e32 v12, v72, v56
	v_fmac_f32_e32 v12, v73, v57
	ds_read_b128 v[58:61], v20 offset:8192
	ds_read_b128 v[62:65], v20 offset:8208
	ds_read_b128 v[66:69], v20 offset:8224
	ds_read_b128 v[70:73], v20 offset:8240
	s_waitcnt lgkmcnt(4)
	v_fmac_f32_e32 v13, v74, v42
	v_fmac_f32_e32 v13, v75, v43
	v_fmac_f32_e32 v13, v76, v44
	v_fmac_f32_e32 v13, v77, v45
	v_fmac_f32_e32 v13, v78, v46
	v_fmac_f32_e32 v13, v79, v47
	v_fmac_f32_e32 v13, v80, v48
	v_fmac_f32_e32 v13, v81, v49
	v_fmac_f32_e32 v13, v82, v50
	v_fmac_f32_e32 v13, v83, v51
	v_fmac_f32_e32 v13, v84, v52
	v_fmac_f32_e32 v13, v85, v53
	v_fmac_f32_e32 v13, v86, v54
	v_fmac_f32_e32 v13, v87, v55
	v_fmac_f32_e32 v13, v88, v56
	v_fmac_f32_e32 v13, v89, v57
	ds_read_b128 v[74:77], v20 offset:12288
	ds_read_b128 v[78:81], v20 offset:12304
	ds_read_b128 v[82:85], v20 offset:12320
	ds_read_b128 v[86:89], v20 offset:12336
	s_waitcnt lgkmcnt(4)
	v_fmac_f32_e32 v14, v58, v42
	v_fmac_f32_e32 v14, v59, v43
	v_fmac_f32_e32 v14, v60, v44
	v_fmac_f32_e32 v14, v61, v45
	v_fmac_f32_e32 v14, v62, v46
	v_fmac_f32_e32 v14, v63, v47
	v_fmac_f32_e32 v14, v64, v48
	v_fmac_f32_e32 v14, v65, v49
	v_fmac_f32_e32 v14, v66, v50
	v_fmac_f32_e32 v14, v67, v51
	v_fmac_f32_e32 v14, v68, v52
	v_fmac_f32_e32 v14, v69, v53
	v_fmac_f32_e32 v14, v70, v54
	v_fmac_f32_e32 v14, v71, v55
	v_fmac_f32_e32 v14, v72, v56
	v_fmac_f32_e32 v14, v73, v57
	ds_read_b128 v[58:61], v20 offset:16384
	ds_read_b128 v[62:65], v20 offset:16400
	ds_read_b128 v[66:69], v20 offset:16416
	ds_read_b128 v[70:73], v20 offset:16432
	s_waitcnt lgkmcnt(4)
	v_fmac_f32_e32 v15, v74, v42
	v_fmac_f32_e32 v15, v75, v43
	v_fmac_f32_e32 v15, v76, v44
	v_fmac_f32_e32 v15, v77, v45
	v_fmac_f32_e32 v15, v78, v46
	v_fmac_f32_e32 v15, v79, v47
	v_fmac_f32_e32 v15, v80, v48
	v_fmac_f32_e32 v15, v81, v49
	v_fmac_f32_e32 v15, v82, v50
	v_fmac_f32_e32 v15, v83, v51
	v_fmac_f32_e32 v15, v84, v52
	v_fmac_f32_e32 v15, v85, v53
	v_fmac_f32_e32 v15, v86, v54
	v_fmac_f32_e32 v15, v87, v55
	v_fmac_f32_e32 v15, v88, v56
	v_fmac_f32_e32 v15, v89, v57
	ds_read_b128 v[74:77], v20 offset:20480
	ds_read_b128 v[78:81], v20 offset:20496
	ds_read_b128 v[82:85], v20 offset:20512
	ds_read_b128 v[86:89], v20 offset:20528
	s_waitcnt lgkmcnt(4)
	v_fmac_f32_e32 v16, v58, v42
	v_fmac_f32_e32 v16, v59, v43
	v_fmac_f32_e32 v16, v60, v44
	v_fmac_f32_e32 v16, v61, v45
	v_fmac_f32_e32 v16, v62, v46
	v_fmac_f32_e32 v16, v63, v47
	v_fmac_f32_e32 v16, v64, v48
	v_fmac_f32_e32 v16, v65, v49
	v_fmac_f32_e32 v16, v66, v50
	v_fmac_f32_e32 v16, v67, v51
	v_fmac_f32_e32 v16, v68, v52
	v_fmac_f32_e32 v16, v69, v53
	v_fmac_f32_e32 v16, v70, v54
	v_fmac_f32_e32 v16, v71, v55
	v_fmac_f32_e32 v16, v72, v56
	v_fmac_f32_e32 v16, v73, v57
	ds_read_b128 v[58:61], v20 offset:24576
	ds_read_b128 v[62:65], v20 offset:24592
	ds_read_b128 v[66:69], v20 offset:24608
	ds_read_b128 v[70:73], v20 offset:24624
	s_waitcnt lgkmcnt(4)
	v_fmac_f32_e32 v17, v74, v42
	v_fmac_f32_e32 v17, v75, v43
	v_fmac_f32_e32 v17, v76, v44
	v_fmac_f32_e32 v17, v77, v45
	v_fmac_f32_e32 v17, v78, v46
	v_fmac_f32_e32 v17, v79, v47
	v_fmac_f32_e32 v17, v80, v48
	v_fmac_f32_e32 v17, v81, v49
	v_fmac_f32_e32 v17, v82, v50
	v_fmac_f32_e32 v17, v83, v51
	v_fmac_f32_e32 v17, v84, v52
	v_fmac_f32_e32 v17, v85, v53
	v_fmac_f32_e32 v17, v86, v54
	v_fmac_f32_e32 v17, v87, v55
	v_fmac_f32_e32 v17, v88, v56
	v_fmac_f32_e32 v17, v89, v57
	ds_read_b128 v[74:77], v20 offset:28672
	ds_read_b128 v[78:81], v20 offset:28688
	ds_read_b128 v[82:85], v20 offset:28704
	ds_read_b128 v[86:89], v20 offset:28720
	s_waitcnt lgkmcnt(4)
	v_fmac_f32_e32 v10, v58, v42
	v_fmac_f32_e32 v10, v59, v43
	v_fmac_f32_e32 v10, v60, v44
	v_fmac_f32_e32 v10, v61, v45
	v_fmac_f32_e32 v10, v62, v46
	v_fmac_f32_e32 v10, v63, v47
	v_fmac_f32_e32 v10, v64, v48
	v_fmac_f32_e32 v10, v65, v49
	v_fmac_f32_e32 v10, v66, v50
	v_fmac_f32_e32 v10, v67, v51
	v_fmac_f32_e32 v10, v68, v52
	v_fmac_f32_e32 v10, v69, v53
	v_fmac_f32_e32 v10, v70, v54
	v_fmac_f32_e32 v10, v71, v55
	v_fmac_f32_e32 v10, v72, v56
	v_fmac_f32_e32 v10, v73, v57
	s_waitcnt lgkmcnt(0)
	v_fmac_f32_e32 v11, v74, v42
	v_fmac_f32_e32 v11, v75, v43
	v_fmac_f32_e32 v11, v76, v44
	v_fmac_f32_e32 v11, v77, v45
	v_fmac_f32_e32 v11, v78, v46
	v_fmac_f32_e32 v11, v79, v47
	v_fmac_f32_e32 v11, v80, v48
	v_fmac_f32_e32 v11, v81, v49
	v_fmac_f32_e32 v11, v82, v50
	v_fmac_f32_e32 v11, v83, v51
	v_fmac_f32_e32 v11, v84, v52
	v_fmac_f32_e32 v11, v85, v53
	v_fmac_f32_e32 v11, v86, v54
	v_fmac_f32_e32 v11, v87, v55
	v_fmac_f32_e32 v11, v88, v56
	v_fmac_f32_e32 v11, v89, v57
	v_mov_b32_e32 v20, s33
	s_add_i32 s33, s33, 64
	ds_read_b128 v[58:61], v20 offset:0
	ds_read_b128 v[62:65], v20 offset:16
	ds_read_b128 v[66:69], v20 offset:32
	ds_read_b128 v[70:73], v20 offset:48
	global_load_dword v42, v[18:19], off
	v_lshl_add_u64 v[18:19], v[18:19], 0, s[34:35]
	global_load_dword v43, v[18:19], off
	v_lshl_add_u64 v[18:19], v[18:19], 0, s[34:35]
	global_load_dword v44, v[18:19], off
	v_lshl_add_u64 v[18:19], v[18:19], 0, s[34:35]
	global_load_dword v45, v[18:19], off
	v_lshl_add_u64 v[18:19], v[18:19], 0, s[34:35]
	global_load_dword v46, v[18:19], off
	v_lshl_add_u64 v[18:19], v[18:19], 0, s[34:35]
	global_load_dword v47, v[18:19], off
	v_lshl_add_u64 v[18:19], v[18:19], 0, s[34:35]
	global_load_dword v48, v[18:19], off
	v_lshl_add_u64 v[18:19], v[18:19], 0, s[34:35]
	global_load_dword v49, v[18:19], off
	v_lshl_add_u64 v[18:19], v[18:19], 0, s[34:35]
	global_load_dword v50, v[18:19], off
	v_lshl_add_u64 v[18:19], v[18:19], 0, s[34:35]
	global_load_dword v51, v[18:19], off
	v_lshl_add_u64 v[18:19], v[18:19], 0, s[34:35]
	global_load_dword v52, v[18:19], off
	v_lshl_add_u64 v[18:19], v[18:19], 0, s[34:35]
	global_load_dword v53, v[18:19], off
	v_lshl_add_u64 v[18:19], v[18:19], 0, s[34:35]
	global_load_dword v54, v[18:19], off
	v_lshl_add_u64 v[18:19], v[18:19], 0, s[34:35]
	global_load_dword v55, v[18:19], off
	v_lshl_add_u64 v[18:19], v[18:19], 0, s[34:35]
	global_load_dword v56, v[18:19], off
	v_lshl_add_u64 v[18:19], v[18:19], 0, s[34:35]
	global_load_dword v57, v[18:19], off
	v_lshl_add_u64 v[18:19], v[18:19], 0, s[34:35]
	s_waitcnt vmcnt(16)
	ds_read_b128 v[74:77], v20 offset:4096
	ds_read_b128 v[78:81], v20 offset:4112
	ds_read_b128 v[82:85], v20 offset:4128
	ds_read_b128 v[86:89], v20 offset:4144
	s_waitcnt lgkmcnt(4)
	v_fmac_f32_e32 v12, v58, v26
	v_fmac_f32_e32 v12, v59, v27
	v_fmac_f32_e32 v12, v60, v28
	v_fmac_f32_e32 v12, v61, v29
	v_fmac_f32_e32 v12, v62, v30
	v_fmac_f32_e32 v12, v63, v31
	v_fmac_f32_e32 v12, v64, v32
	v_fmac_f32_e32 v12, v65, v33
	v_fmac_f32_e32 v12, v66, v34
	v_fmac_f32_e32 v12, v67, v35
	v_fmac_f32_e32 v12, v68, v36
	v_fmac_f32_e32 v12, v69, v37
	v_fmac_f32_e32 v12, v70, v38
	v_fmac_f32_e32 v12, v71, v39
	v_fmac_f32_e32 v12, v72, v40
	v_fmac_f32_e32 v12, v73, v41
	ds_read_b128 v[58:61], v20 offset:8192
	ds_read_b128 v[62:65], v20 offset:8208
	ds_read_b128 v[66:69], v20 offset:8224
	ds_read_b128 v[70:73], v20 offset:8240
	s_waitcnt lgkmcnt(4)
	v_fmac_f32_e32 v13, v74, v26
	v_fmac_f32_e32 v13, v75, v27
	v_fmac_f32_e32 v13, v76, v28
	v_fmac_f32_e32 v13, v77, v29
	v_fmac_f32_e32 v13, v78, v30
	v_fmac_f32_e32 v13, v79, v31
	v_fmac_f32_e32 v13, v80, v32
	v_fmac_f32_e32 v13, v81, v33
	v_fmac_f32_e32 v13, v82, v34
	v_fmac_f32_e32 v13, v83, v35
	v_fmac_f32_e32 v13, v84, v36
	v_fmac_f32_e32 v13, v85, v37
	v_fmac_f32_e32 v13, v86, v38
	v_fmac_f32_e32 v13, v87, v39
	v_fmac_f32_e32 v13, v88, v40
	v_fmac_f32_e32 v13, v89, v41
	ds_read_b128 v[74:77], v20 offset:12288
	ds_read_b128 v[78:81], v20 offset:12304
	ds_read_b128 v[82:85], v20 offset:12320
	ds_read_b128 v[86:89], v20 offset:12336
	s_waitcnt lgkmcnt(4)
	v_fmac_f32_e32 v14, v58, v26
	v_fmac_f32_e32 v14, v59, v27
	v_fmac_f32_e32 v14, v60, v28
	v_fmac_f32_e32 v14, v61, v29
	v_fmac_f32_e32 v14, v62, v30
	v_fmac_f32_e32 v14, v63, v31
	v_fmac_f32_e32 v14, v64, v32
	v_fmac_f32_e32 v14, v65, v33
	v_fmac_f32_e32 v14, v66, v34
	v_fmac_f32_e32 v14, v67, v35
	v_fmac_f32_e32 v14, v68, v36
	v_fmac_f32_e32 v14, v69, v37
	v_fmac_f32_e32 v14, v70, v38
	v_fmac_f32_e32 v14, v71, v39
	v_fmac_f32_e32 v14, v72, v40
	v_fmac_f32_e32 v14, v73, v41
	ds_read_b128 v[58:61], v20 offset:16384
	ds_read_b128 v[62:65], v20 offset:16400
	ds_read_b128 v[66:69], v20 offset:16416
	ds_read_b128 v[70:73], v20 offset:16432
	s_waitcnt lgkmcnt(4)
	v_fmac_f32_e32 v15, v74, v26
	v_fmac_f32_e32 v15, v75, v27
	v_fmac_f32_e32 v15, v76, v28
	v_fmac_f32_e32 v15, v77, v29
	v_fmac_f32_e32 v15, v78, v30
	v_fmac_f32_e32 v15, v79, v31
	v_fmac_f32_e32 v15, v80, v32
	v_fmac_f32_e32 v15, v81, v33
	v_fmac_f32_e32 v15, v82, v34
	v_fmac_f32_e32 v15, v83, v35
	v_fmac_f32_e32 v15, v84, v36
	v_fmac_f32_e32 v15, v85, v37
	v_fmac_f32_e32 v15, v86, v38
	v_fmac_f32_e32 v15, v87, v39
	v_fmac_f32_e32 v15, v88, v40
	v_fmac_f32_e32 v15, v89, v41
	ds_read_b128 v[74:77], v20 offset:20480
	ds_read_b128 v[78:81], v20 offset:20496
	ds_read_b128 v[82:85], v20 offset:20512
	ds_read_b128 v[86:89], v20 offset:20528
	s_waitcnt lgkmcnt(4)
	v_fmac_f32_e32 v16, v58, v26
	v_fmac_f32_e32 v16, v59, v27
	v_fmac_f32_e32 v16, v60, v28
	v_fmac_f32_e32 v16, v61, v29
	v_fmac_f32_e32 v16, v62, v30
	v_fmac_f32_e32 v16, v63, v31
	v_fmac_f32_e32 v16, v64, v32
	v_fmac_f32_e32 v16, v65, v33
	v_fmac_f32_e32 v16, v66, v34
	v_fmac_f32_e32 v16, v67, v35
	v_fmac_f32_e32 v16, v68, v36
	v_fmac_f32_e32 v16, v69, v37
	v_fmac_f32_e32 v16, v70, v38
	v_fmac_f32_e32 v16, v71, v39
	v_fmac_f32_e32 v16, v72, v40
	v_fmac_f32_e32 v16, v73, v41
	ds_read_b128 v[58:61], v20 offset:24576
	ds_read_b128 v[62:65], v20 offset:24592
	ds_read_b128 v[66:69], v20 offset:24608
	ds_read_b128 v[70:73], v20 offset:24624
	s_waitcnt lgkmcnt(4)
	v_fmac_f32_e32 v17, v74, v26
	v_fmac_f32_e32 v17, v75, v27
	v_fmac_f32_e32 v17, v76, v28
	v_fmac_f32_e32 v17, v77, v29
	v_fmac_f32_e32 v17, v78, v30
	v_fmac_f32_e32 v17, v79, v31
	v_fmac_f32_e32 v17, v80, v32
	v_fmac_f32_e32 v17, v81, v33
	v_fmac_f32_e32 v17, v82, v34
	v_fmac_f32_e32 v17, v83, v35
	v_fmac_f32_e32 v17, v84, v36
	v_fmac_f32_e32 v17, v85, v37
	v_fmac_f32_e32 v17, v86, v38
	v_fmac_f32_e32 v17, v87, v39
	v_fmac_f32_e32 v17, v88, v40
	v_fmac_f32_e32 v17, v89, v41
	ds_read_b128 v[74:77], v20 offset:28672
	ds_read_b128 v[78:81], v20 offset:28688
	ds_read_b128 v[82:85], v20 offset:28704
	ds_read_b128 v[86:89], v20 offset:28720
	s_waitcnt lgkmcnt(4)
	v_fmac_f32_e32 v10, v58, v26
	v_fmac_f32_e32 v10, v59, v27
	v_fmac_f32_e32 v10, v60, v28
	v_fmac_f32_e32 v10, v61, v29
	v_fmac_f32_e32 v10, v62, v30
	v_fmac_f32_e32 v10, v63, v31
	v_fmac_f32_e32 v10, v64, v32
	v_fmac_f32_e32 v10, v65, v33
	v_fmac_f32_e32 v10, v66, v34
	v_fmac_f32_e32 v10, v67, v35
	v_fmac_f32_e32 v10, v68, v36
	v_fmac_f32_e32 v10, v69, v37
	v_fmac_f32_e32 v10, v70, v38
	v_fmac_f32_e32 v10, v71, v39
	v_fmac_f32_e32 v10, v72, v40
	v_fmac_f32_e32 v10, v73, v41
	s_waitcnt lgkmcnt(0)
	v_fmac_f32_e32 v11, v74, v26
	v_fmac_f32_e32 v11, v75, v27
	v_fmac_f32_e32 v11, v76, v28
	v_fmac_f32_e32 v11, v77, v29
	v_fmac_f32_e32 v11, v78, v30
	v_fmac_f32_e32 v11, v79, v31
	v_fmac_f32_e32 v11, v80, v32
	v_fmac_f32_e32 v11, v81, v33
	v_fmac_f32_e32 v11, v82, v34
	v_fmac_f32_e32 v11, v83, v35
	v_fmac_f32_e32 v11, v84, v36
	v_fmac_f32_e32 v11, v85, v37
	v_fmac_f32_e32 v11, v86, v38
	v_fmac_f32_e32 v11, v87, v39
	v_fmac_f32_e32 v11, v88, v40
	v_fmac_f32_e32 v11, v89, v41
	v_mov_b32_e32 v20, s33
	s_add_i32 s33, s33, 64
	ds_read_b128 v[58:61], v20 offset:0
	ds_read_b128 v[62:65], v20 offset:16
	ds_read_b128 v[66:69], v20 offset:32
	ds_read_b128 v[70:73], v20 offset:48
	global_load_dword v26, v[18:19], off
	v_lshl_add_u64 v[18:19], v[18:19], 0, s[34:35]
	global_load_dword v27, v[18:19], off
	v_lshl_add_u64 v[18:19], v[18:19], 0, s[34:35]
	global_load_dword v28, v[18:19], off
	v_lshl_add_u64 v[18:19], v[18:19], 0, s[34:35]
	global_load_dword v29, v[18:19], off
	v_lshl_add_u64 v[18:19], v[18:19], 0, s[34:35]
	global_load_dword v30, v[18:19], off
	v_lshl_add_u64 v[18:19], v[18:19], 0, s[34:35]
	global_load_dword v31, v[18:19], off
	v_lshl_add_u64 v[18:19], v[18:19], 0, s[34:35]
	global_load_dword v32, v[18:19], off
	v_lshl_add_u64 v[18:19], v[18:19], 0, s[34:35]
	global_load_dword v33, v[18:19], off
	v_lshl_add_u64 v[18:19], v[18:19], 0, s[34:35]
	global_load_dword v34, v[18:19], off
	v_lshl_add_u64 v[18:19], v[18:19], 0, s[34:35]
	global_load_dword v35, v[18:19], off
	v_lshl_add_u64 v[18:19], v[18:19], 0, s[34:35]
	global_load_dword v36, v[18:19], off
	v_lshl_add_u64 v[18:19], v[18:19], 0, s[34:35]
	global_load_dword v37, v[18:19], off
	v_lshl_add_u64 v[18:19], v[18:19], 0, s[34:35]
	global_load_dword v38, v[18:19], off
	v_lshl_add_u64 v[18:19], v[18:19], 0, s[34:35]
	global_load_dword v39, v[18:19], off
	v_lshl_add_u64 v[18:19], v[18:19], 0, s[34:35]
	global_load_dword v40, v[18:19], off
	v_lshl_add_u64 v[18:19], v[18:19], 0, s[34:35]
	global_load_dword v41, v[18:19], off
	v_lshl_add_u64 v[18:19], v[18:19], 0, s[34:35]
	s_waitcnt vmcnt(16)
	ds_read_b128 v[74:77], v20 offset:4096
	ds_read_b128 v[78:81], v20 offset:4112
	ds_read_b128 v[82:85], v20 offset:4128
	ds_read_b128 v[86:89], v20 offset:4144
	s_waitcnt lgkmcnt(4)
	v_fmac_f32_e32 v12, v58, v42
	v_fmac_f32_e32 v12, v59, v43
	v_fmac_f32_e32 v12, v60, v44
	v_fmac_f32_e32 v12, v61, v45
	v_fmac_f32_e32 v12, v62, v46
	v_fmac_f32_e32 v12, v63, v47
	v_fmac_f32_e32 v12, v64, v48
	v_fmac_f32_e32 v12, v65, v49
	v_fmac_f32_e32 v12, v66, v50
	v_fmac_f32_e32 v12, v67, v51
	v_fmac_f32_e32 v12, v68, v52
	v_fmac_f32_e32 v12, v69, v53
	v_fmac_f32_e32 v12, v70, v54
	v_fmac_f32_e32 v12, v71, v55
	v_fmac_f32_e32 v12, v72, v56
	v_fmac_f32_e32 v12, v73, v57
	ds_read_b128 v[58:61], v20 offset:8192
	ds_read_b128 v[62:65], v20 offset:8208
	ds_read_b128 v[66:69], v20 offset:8224
	ds_read_b128 v[70:73], v20 offset:8240
	s_waitcnt lgkmcnt(4)
	v_fmac_f32_e32 v13, v74, v42
	v_fmac_f32_e32 v13, v75, v43
	v_fmac_f32_e32 v13, v76, v44
	v_fmac_f32_e32 v13, v77, v45
	v_fmac_f32_e32 v13, v78, v46
	v_fmac_f32_e32 v13, v79, v47
	v_fmac_f32_e32 v13, v80, v48
	v_fmac_f32_e32 v13, v81, v49
	v_fmac_f32_e32 v13, v82, v50
	v_fmac_f32_e32 v13, v83, v51
	v_fmac_f32_e32 v13, v84, v52
	v_fmac_f32_e32 v13, v85, v53
	v_fmac_f32_e32 v13, v86, v54
	v_fmac_f32_e32 v13, v87, v55
	v_fmac_f32_e32 v13, v88, v56
	v_fmac_f32_e32 v13, v89, v57
	ds_read_b128 v[74:77], v20 offset:12288
	ds_read_b128 v[78:81], v20 offset:12304
	ds_read_b128 v[82:85], v20 offset:12320
	ds_read_b128 v[86:89], v20 offset:12336
	s_waitcnt lgkmcnt(4)
	v_fmac_f32_e32 v14, v58, v42
	v_fmac_f32_e32 v14, v59, v43
	v_fmac_f32_e32 v14, v60, v44
	v_fmac_f32_e32 v14, v61, v45
	v_fmac_f32_e32 v14, v62, v46
	v_fmac_f32_e32 v14, v63, v47
	v_fmac_f32_e32 v14, v64, v48
	v_fmac_f32_e32 v14, v65, v49
	v_fmac_f32_e32 v14, v66, v50
	v_fmac_f32_e32 v14, v67, v51
	v_fmac_f32_e32 v14, v68, v52
	v_fmac_f32_e32 v14, v69, v53
	v_fmac_f32_e32 v14, v70, v54
	v_fmac_f32_e32 v14, v71, v55
	v_fmac_f32_e32 v14, v72, v56
	v_fmac_f32_e32 v14, v73, v57
	ds_read_b128 v[58:61], v20 offset:16384
	ds_read_b128 v[62:65], v20 offset:16400
	ds_read_b128 v[66:69], v20 offset:16416
	ds_read_b128 v[70:73], v20 offset:16432
	s_waitcnt lgkmcnt(4)
	v_fmac_f32_e32 v15, v74, v42
	v_fmac_f32_e32 v15, v75, v43
	v_fmac_f32_e32 v15, v76, v44
	v_fmac_f32_e32 v15, v77, v45
	v_fmac_f32_e32 v15, v78, v46
	v_fmac_f32_e32 v15, v79, v47
	v_fmac_f32_e32 v15, v80, v48
	v_fmac_f32_e32 v15, v81, v49
	v_fmac_f32_e32 v15, v82, v50
	v_fmac_f32_e32 v15, v83, v51
	v_fmac_f32_e32 v15, v84, v52
	v_fmac_f32_e32 v15, v85, v53
	v_fmac_f32_e32 v15, v86, v54
	v_fmac_f32_e32 v15, v87, v55
	v_fmac_f32_e32 v15, v88, v56
	v_fmac_f32_e32 v15, v89, v57
	ds_read_b128 v[74:77], v20 offset:20480
	ds_read_b128 v[78:81], v20 offset:20496
	ds_read_b128 v[82:85], v20 offset:20512
	ds_read_b128 v[86:89], v20 offset:20528
	s_waitcnt lgkmcnt(4)
	v_fmac_f32_e32 v16, v58, v42
	v_fmac_f32_e32 v16, v59, v43
	v_fmac_f32_e32 v16, v60, v44
	v_fmac_f32_e32 v16, v61, v45
	v_fmac_f32_e32 v16, v62, v46
	v_fmac_f32_e32 v16, v63, v47
	v_fmac_f32_e32 v16, v64, v48
	v_fmac_f32_e32 v16, v65, v49
	v_fmac_f32_e32 v16, v66, v50
	v_fmac_f32_e32 v16, v67, v51
	v_fmac_f32_e32 v16, v68, v52
	v_fmac_f32_e32 v16, v69, v53
	v_fmac_f32_e32 v16, v70, v54
	v_fmac_f32_e32 v16, v71, v55
	v_fmac_f32_e32 v16, v72, v56
	v_fmac_f32_e32 v16, v73, v57
	ds_read_b128 v[58:61], v20 offset:24576
	ds_read_b128 v[62:65], v20 offset:24592
	ds_read_b128 v[66:69], v20 offset:24608
	ds_read_b128 v[70:73], v20 offset:24624
	s_waitcnt lgkmcnt(4)
	v_fmac_f32_e32 v17, v74, v42
	v_fmac_f32_e32 v17, v75, v43
	v_fmac_f32_e32 v17, v76, v44
	v_fmac_f32_e32 v17, v77, v45
	v_fmac_f32_e32 v17, v78, v46
	v_fmac_f32_e32 v17, v79, v47
	v_fmac_f32_e32 v17, v80, v48
	v_fmac_f32_e32 v17, v81, v49
	v_fmac_f32_e32 v17, v82, v50
	v_fmac_f32_e32 v17, v83, v51
	v_fmac_f32_e32 v17, v84, v52
	v_fmac_f32_e32 v17, v85, v53
	v_fmac_f32_e32 v17, v86, v54
	v_fmac_f32_e32 v17, v87, v55
	v_fmac_f32_e32 v17, v88, v56
	v_fmac_f32_e32 v17, v89, v57
	ds_read_b128 v[74:77], v20 offset:28672
	ds_read_b128 v[78:81], v20 offset:28688
	ds_read_b128 v[82:85], v20 offset:28704
	ds_read_b128 v[86:89], v20 offset:28720
	s_waitcnt lgkmcnt(4)
	v_fmac_f32_e32 v10, v58, v42
	v_fmac_f32_e32 v10, v59, v43
	v_fmac_f32_e32 v10, v60, v44
	v_fmac_f32_e32 v10, v61, v45
	v_fmac_f32_e32 v10, v62, v46
	v_fmac_f32_e32 v10, v63, v47
	v_fmac_f32_e32 v10, v64, v48
	v_fmac_f32_e32 v10, v65, v49
	v_fmac_f32_e32 v10, v66, v50
	v_fmac_f32_e32 v10, v67, v51
	v_fmac_f32_e32 v10, v68, v52
	v_fmac_f32_e32 v10, v69, v53
	v_fmac_f32_e32 v10, v70, v54
	v_fmac_f32_e32 v10, v71, v55
	v_fmac_f32_e32 v10, v72, v56
	v_fmac_f32_e32 v10, v73, v57
	s_waitcnt lgkmcnt(0)
	v_fmac_f32_e32 v11, v74, v42
	v_fmac_f32_e32 v11, v75, v43
	v_fmac_f32_e32 v11, v76, v44
	v_fmac_f32_e32 v11, v77, v45
	v_fmac_f32_e32 v11, v78, v46
	v_fmac_f32_e32 v11, v79, v47
	v_fmac_f32_e32 v11, v80, v48
	v_fmac_f32_e32 v11, v81, v49
	v_fmac_f32_e32 v11, v82, v50
	v_fmac_f32_e32 v11, v83, v51
	v_fmac_f32_e32 v11, v84, v52
	v_fmac_f32_e32 v11, v85, v53
	v_fmac_f32_e32 v11, v86, v54
	v_fmac_f32_e32 v11, v87, v55
	v_fmac_f32_e32 v11, v88, v56
	v_fmac_f32_e32 v11, v89, v57
	v_mov_b32_e32 v20, s33
	s_add_i32 s33, s33, 64
	ds_read_b128 v[58:61], v20 offset:0
	ds_read_b128 v[62:65], v20 offset:16
	ds_read_b128 v[66:69], v20 offset:32
	ds_read_b128 v[70:73], v20 offset:48
	global_load_dword v42, v[18:19], off
	v_lshl_add_u64 v[18:19], v[18:19], 0, s[34:35]
	global_load_dword v43, v[18:19], off
	v_lshl_add_u64 v[18:19], v[18:19], 0, s[34:35]
	global_load_dword v44, v[18:19], off
	v_lshl_add_u64 v[18:19], v[18:19], 0, s[34:35]
	global_load_dword v45, v[18:19], off
	v_lshl_add_u64 v[18:19], v[18:19], 0, s[34:35]
	global_load_dword v46, v[18:19], off
	v_lshl_add_u64 v[18:19], v[18:19], 0, s[34:35]
	global_load_dword v47, v[18:19], off
	v_lshl_add_u64 v[18:19], v[18:19], 0, s[34:35]
	global_load_dword v48, v[18:19], off
	v_lshl_add_u64 v[18:19], v[18:19], 0, s[34:35]
	global_load_dword v49, v[18:19], off
	v_lshl_add_u64 v[18:19], v[18:19], 0, s[34:35]
	global_load_dword v50, v[18:19], off
	v_lshl_add_u64 v[18:19], v[18:19], 0, s[34:35]
	global_load_dword v51, v[18:19], off
	v_lshl_add_u64 v[18:19], v[18:19], 0, s[34:35]
	global_load_dword v52, v[18:19], off
	v_lshl_add_u64 v[18:19], v[18:19], 0, s[34:35]
	global_load_dword v53, v[18:19], off
	v_lshl_add_u64 v[18:19], v[18:19], 0, s[34:35]
	global_load_dword v54, v[18:19], off
	v_lshl_add_u64 v[18:19], v[18:19], 0, s[34:35]
	global_load_dword v55, v[18:19], off
	v_lshl_add_u64 v[18:19], v[18:19], 0, s[34:35]
	global_load_dword v56, v[18:19], off
	v_lshl_add_u64 v[18:19], v[18:19], 0, s[34:35]
	global_load_dword v57, v[18:19], off
	v_lshl_add_u64 v[18:19], v[18:19], 0, s[34:35]
	s_waitcnt vmcnt(16)
	ds_read_b128 v[74:77], v20 offset:4096
	ds_read_b128 v[78:81], v20 offset:4112
	ds_read_b128 v[82:85], v20 offset:4128
	ds_read_b128 v[86:89], v20 offset:4144
	s_waitcnt lgkmcnt(4)
	v_fmac_f32_e32 v12, v58, v26
	v_fmac_f32_e32 v12, v59, v27
	v_fmac_f32_e32 v12, v60, v28
	v_fmac_f32_e32 v12, v61, v29
	v_fmac_f32_e32 v12, v62, v30
	v_fmac_f32_e32 v12, v63, v31
	v_fmac_f32_e32 v12, v64, v32
	v_fmac_f32_e32 v12, v65, v33
	v_fmac_f32_e32 v12, v66, v34
	v_fmac_f32_e32 v12, v67, v35
	v_fmac_f32_e32 v12, v68, v36
	v_fmac_f32_e32 v12, v69, v37
	v_fmac_f32_e32 v12, v70, v38
	v_fmac_f32_e32 v12, v71, v39
	v_fmac_f32_e32 v12, v72, v40
	v_fmac_f32_e32 v12, v73, v41
	ds_read_b128 v[58:61], v20 offset:8192
	ds_read_b128 v[62:65], v20 offset:8208
	ds_read_b128 v[66:69], v20 offset:8224
	ds_read_b128 v[70:73], v20 offset:8240
	s_waitcnt lgkmcnt(4)
	v_fmac_f32_e32 v13, v74, v26
	v_fmac_f32_e32 v13, v75, v27
	v_fmac_f32_e32 v13, v76, v28
	v_fmac_f32_e32 v13, v77, v29
	v_fmac_f32_e32 v13, v78, v30
	v_fmac_f32_e32 v13, v79, v31
	v_fmac_f32_e32 v13, v80, v32
	v_fmac_f32_e32 v13, v81, v33
	v_fmac_f32_e32 v13, v82, v34
	v_fmac_f32_e32 v13, v83, v35
	v_fmac_f32_e32 v13, v84, v36
	v_fmac_f32_e32 v13, v85, v37
	v_fmac_f32_e32 v13, v86, v38
	v_fmac_f32_e32 v13, v87, v39
	v_fmac_f32_e32 v13, v88, v40
	v_fmac_f32_e32 v13, v89, v41
	ds_read_b128 v[74:77], v20 offset:12288
	ds_read_b128 v[78:81], v20 offset:12304
	ds_read_b128 v[82:85], v20 offset:12320
	ds_read_b128 v[86:89], v20 offset:12336
	s_waitcnt lgkmcnt(4)
	v_fmac_f32_e32 v14, v58, v26
	v_fmac_f32_e32 v14, v59, v27
	v_fmac_f32_e32 v14, v60, v28
	v_fmac_f32_e32 v14, v61, v29
	v_fmac_f32_e32 v14, v62, v30
	v_fmac_f32_e32 v14, v63, v31
	v_fmac_f32_e32 v14, v64, v32
	v_fmac_f32_e32 v14, v65, v33
	v_fmac_f32_e32 v14, v66, v34
	v_fmac_f32_e32 v14, v67, v35
	v_fmac_f32_e32 v14, v68, v36
	v_fmac_f32_e32 v14, v69, v37
	v_fmac_f32_e32 v14, v70, v38
	v_fmac_f32_e32 v14, v71, v39
	v_fmac_f32_e32 v14, v72, v40
	v_fmac_f32_e32 v14, v73, v41
	ds_read_b128 v[58:61], v20 offset:16384
	ds_read_b128 v[62:65], v20 offset:16400
	ds_read_b128 v[66:69], v20 offset:16416
	ds_read_b128 v[70:73], v20 offset:16432
	s_waitcnt lgkmcnt(4)
	v_fmac_f32_e32 v15, v74, v26
	v_fmac_f32_e32 v15, v75, v27
	v_fmac_f32_e32 v15, v76, v28
	v_fmac_f32_e32 v15, v77, v29
	v_fmac_f32_e32 v15, v78, v30
	v_fmac_f32_e32 v15, v79, v31
	v_fmac_f32_e32 v15, v80, v32
	v_fmac_f32_e32 v15, v81, v33
	v_fmac_f32_e32 v15, v82, v34
	v_fmac_f32_e32 v15, v83, v35
	v_fmac_f32_e32 v15, v84, v36
	v_fmac_f32_e32 v15, v85, v37
	v_fmac_f32_e32 v15, v86, v38
	v_fmac_f32_e32 v15, v87, v39
	v_fmac_f32_e32 v15, v88, v40
	v_fmac_f32_e32 v15, v89, v41
	ds_read_b128 v[74:77], v20 offset:20480
	ds_read_b128 v[78:81], v20 offset:20496
	ds_read_b128 v[82:85], v20 offset:20512
	ds_read_b128 v[86:89], v20 offset:20528
	s_waitcnt lgkmcnt(4)
	v_fmac_f32_e32 v16, v58, v26
	v_fmac_f32_e32 v16, v59, v27
	v_fmac_f32_e32 v16, v60, v28
	v_fmac_f32_e32 v16, v61, v29
	v_fmac_f32_e32 v16, v62, v30
	v_fmac_f32_e32 v16, v63, v31
	v_fmac_f32_e32 v16, v64, v32
	v_fmac_f32_e32 v16, v65, v33
	v_fmac_f32_e32 v16, v66, v34
	v_fmac_f32_e32 v16, v67, v35
	v_fmac_f32_e32 v16, v68, v36
	v_fmac_f32_e32 v16, v69, v37
	v_fmac_f32_e32 v16, v70, v38
	v_fmac_f32_e32 v16, v71, v39
	v_fmac_f32_e32 v16, v72, v40
	v_fmac_f32_e32 v16, v73, v41
	ds_read_b128 v[58:61], v20 offset:24576
	ds_read_b128 v[62:65], v20 offset:24592
	ds_read_b128 v[66:69], v20 offset:24608
	ds_read_b128 v[70:73], v20 offset:24624
	s_waitcnt lgkmcnt(4)
	v_fmac_f32_e32 v17, v74, v26
	v_fmac_f32_e32 v17, v75, v27
	v_fmac_f32_e32 v17, v76, v28
	v_fmac_f32_e32 v17, v77, v29
	v_fmac_f32_e32 v17, v78, v30
	v_fmac_f32_e32 v17, v79, v31
	v_fmac_f32_e32 v17, v80, v32
	v_fmac_f32_e32 v17, v81, v33
	v_fmac_f32_e32 v17, v82, v34
	v_fmac_f32_e32 v17, v83, v35
	v_fmac_f32_e32 v17, v84, v36
	v_fmac_f32_e32 v17, v85, v37
	v_fmac_f32_e32 v17, v86, v38
	v_fmac_f32_e32 v17, v87, v39
	v_fmac_f32_e32 v17, v88, v40
	v_fmac_f32_e32 v17, v89, v41
	ds_read_b128 v[74:77], v20 offset:28672
	ds_read_b128 v[78:81], v20 offset:28688
	ds_read_b128 v[82:85], v20 offset:28704
	ds_read_b128 v[86:89], v20 offset:28720
	s_waitcnt lgkmcnt(4)
	v_fmac_f32_e32 v10, v58, v26
	v_fmac_f32_e32 v10, v59, v27
	v_fmac_f32_e32 v10, v60, v28
	v_fmac_f32_e32 v10, v61, v29
	v_fmac_f32_e32 v10, v62, v30
	v_fmac_f32_e32 v10, v63, v31
	v_fmac_f32_e32 v10, v64, v32
	v_fmac_f32_e32 v10, v65, v33
	v_fmac_f32_e32 v10, v66, v34
	v_fmac_f32_e32 v10, v67, v35
	v_fmac_f32_e32 v10, v68, v36
	v_fmac_f32_e32 v10, v69, v37
	v_fmac_f32_e32 v10, v70, v38
	v_fmac_f32_e32 v10, v71, v39
	v_fmac_f32_e32 v10, v72, v40
	v_fmac_f32_e32 v10, v73, v41
	s_waitcnt lgkmcnt(0)
	v_fmac_f32_e32 v11, v74, v26
	v_fmac_f32_e32 v11, v75, v27
	v_fmac_f32_e32 v11, v76, v28
	v_fmac_f32_e32 v11, v77, v29
	v_fmac_f32_e32 v11, v78, v30
	v_fmac_f32_e32 v11, v79, v31
	v_fmac_f32_e32 v11, v80, v32
	v_fmac_f32_e32 v11, v81, v33
	v_fmac_f32_e32 v11, v82, v34
	v_fmac_f32_e32 v11, v83, v35
	v_fmac_f32_e32 v11, v84, v36
	v_fmac_f32_e32 v11, v85, v37
	v_fmac_f32_e32 v11, v86, v38
	v_fmac_f32_e32 v11, v87, v39
	v_fmac_f32_e32 v11, v88, v40
	v_fmac_f32_e32 v11, v89, v41
	v_mov_b32_e32 v20, s33
	s_add_i32 s33, s33, 64
	ds_read_b128 v[58:61], v20 offset:0
	ds_read_b128 v[62:65], v20 offset:16
	ds_read_b128 v[66:69], v20 offset:32
	ds_read_b128 v[70:73], v20 offset:48
	global_load_dword v26, v[18:19], off
	v_lshl_add_u64 v[18:19], v[18:19], 0, s[34:35]
	global_load_dword v27, v[18:19], off
	v_lshl_add_u64 v[18:19], v[18:19], 0, s[34:35]
	global_load_dword v28, v[18:19], off
	v_lshl_add_u64 v[18:19], v[18:19], 0, s[34:35]
	global_load_dword v29, v[18:19], off
	v_lshl_add_u64 v[18:19], v[18:19], 0, s[34:35]
	global_load_dword v30, v[18:19], off
	v_lshl_add_u64 v[18:19], v[18:19], 0, s[34:35]
	global_load_dword v31, v[18:19], off
	v_lshl_add_u64 v[18:19], v[18:19], 0, s[34:35]
	global_load_dword v32, v[18:19], off
	v_lshl_add_u64 v[18:19], v[18:19], 0, s[34:35]
	global_load_dword v33, v[18:19], off
	v_lshl_add_u64 v[18:19], v[18:19], 0, s[34:35]
	global_load_dword v34, v[18:19], off
	v_lshl_add_u64 v[18:19], v[18:19], 0, s[34:35]
	global_load_dword v35, v[18:19], off
	v_lshl_add_u64 v[18:19], v[18:19], 0, s[34:35]
	global_load_dword v36, v[18:19], off
	v_lshl_add_u64 v[18:19], v[18:19], 0, s[34:35]
	global_load_dword v37, v[18:19], off
	v_lshl_add_u64 v[18:19], v[18:19], 0, s[34:35]
	global_load_dword v38, v[18:19], off
	v_lshl_add_u64 v[18:19], v[18:19], 0, s[34:35]
	global_load_dword v39, v[18:19], off
	v_lshl_add_u64 v[18:19], v[18:19], 0, s[34:35]
	global_load_dword v40, v[18:19], off
	v_lshl_add_u64 v[18:19], v[18:19], 0, s[34:35]
	global_load_dword v41, v[18:19], off
	v_lshl_add_u64 v[18:19], v[18:19], 0, s[34:35]
	s_waitcnt vmcnt(16)
	ds_read_b128 v[74:77], v20 offset:4096
	ds_read_b128 v[78:81], v20 offset:4112
	ds_read_b128 v[82:85], v20 offset:4128
	ds_read_b128 v[86:89], v20 offset:4144
	s_waitcnt lgkmcnt(4)
	v_fmac_f32_e32 v12, v58, v42
	v_fmac_f32_e32 v12, v59, v43
	v_fmac_f32_e32 v12, v60, v44
	v_fmac_f32_e32 v12, v61, v45
	v_fmac_f32_e32 v12, v62, v46
	v_fmac_f32_e32 v12, v63, v47
	v_fmac_f32_e32 v12, v64, v48
	v_fmac_f32_e32 v12, v65, v49
	v_fmac_f32_e32 v12, v66, v50
	v_fmac_f32_e32 v12, v67, v51
	v_fmac_f32_e32 v12, v68, v52
	v_fmac_f32_e32 v12, v69, v53
	v_fmac_f32_e32 v12, v70, v54
	v_fmac_f32_e32 v12, v71, v55
	v_fmac_f32_e32 v12, v72, v56
	v_fmac_f32_e32 v12, v73, v57
	ds_read_b128 v[58:61], v20 offset:8192
	ds_read_b128 v[62:65], v20 offset:8208
	ds_read_b128 v[66:69], v20 offset:8224
	ds_read_b128 v[70:73], v20 offset:8240
	s_waitcnt lgkmcnt(4)
	v_fmac_f32_e32 v13, v74, v42
	v_fmac_f32_e32 v13, v75, v43
	v_fmac_f32_e32 v13, v76, v44
	v_fmac_f32_e32 v13, v77, v45
	v_fmac_f32_e32 v13, v78, v46
	v_fmac_f32_e32 v13, v79, v47
	v_fmac_f32_e32 v13, v80, v48
	v_fmac_f32_e32 v13, v81, v49
	v_fmac_f32_e32 v13, v82, v50
	v_fmac_f32_e32 v13, v83, v51
	v_fmac_f32_e32 v13, v84, v52
	v_fmac_f32_e32 v13, v85, v53
	v_fmac_f32_e32 v13, v86, v54
	v_fmac_f32_e32 v13, v87, v55
	v_fmac_f32_e32 v13, v88, v56
	v_fmac_f32_e32 v13, v89, v57
	ds_read_b128 v[74:77], v20 offset:12288
	ds_read_b128 v[78:81], v20 offset:12304
	ds_read_b128 v[82:85], v20 offset:12320
	ds_read_b128 v[86:89], v20 offset:12336
	s_waitcnt lgkmcnt(4)
	v_fmac_f32_e32 v14, v58, v42
	v_fmac_f32_e32 v14, v59, v43
	v_fmac_f32_e32 v14, v60, v44
	v_fmac_f32_e32 v14, v61, v45
	v_fmac_f32_e32 v14, v62, v46
	v_fmac_f32_e32 v14, v63, v47
	v_fmac_f32_e32 v14, v64, v48
	v_fmac_f32_e32 v14, v65, v49
	v_fmac_f32_e32 v14, v66, v50
	v_fmac_f32_e32 v14, v67, v51
	v_fmac_f32_e32 v14, v68, v52
	v_fmac_f32_e32 v14, v69, v53
	v_fmac_f32_e32 v14, v70, v54
	v_fmac_f32_e32 v14, v71, v55
	v_fmac_f32_e32 v14, v72, v56
	v_fmac_f32_e32 v14, v73, v57
	ds_read_b128 v[58:61], v20 offset:16384
	ds_read_b128 v[62:65], v20 offset:16400
	ds_read_b128 v[66:69], v20 offset:16416
	ds_read_b128 v[70:73], v20 offset:16432
	s_waitcnt lgkmcnt(4)
	v_fmac_f32_e32 v15, v74, v42
	v_fmac_f32_e32 v15, v75, v43
	v_fmac_f32_e32 v15, v76, v44
	v_fmac_f32_e32 v15, v77, v45
	v_fmac_f32_e32 v15, v78, v46
	v_fmac_f32_e32 v15, v79, v47
	v_fmac_f32_e32 v15, v80, v48
	v_fmac_f32_e32 v15, v81, v49
	v_fmac_f32_e32 v15, v82, v50
	v_fmac_f32_e32 v15, v83, v51
	v_fmac_f32_e32 v15, v84, v52
	v_fmac_f32_e32 v15, v85, v53
	v_fmac_f32_e32 v15, v86, v54
	v_fmac_f32_e32 v15, v87, v55
	v_fmac_f32_e32 v15, v88, v56
	v_fmac_f32_e32 v15, v89, v57
	ds_read_b128 v[74:77], v20 offset:20480
	ds_read_b128 v[78:81], v20 offset:20496
	ds_read_b128 v[82:85], v20 offset:20512
	ds_read_b128 v[86:89], v20 offset:20528
	s_waitcnt lgkmcnt(4)
	v_fmac_f32_e32 v16, v58, v42
	v_fmac_f32_e32 v16, v59, v43
	v_fmac_f32_e32 v16, v60, v44
	v_fmac_f32_e32 v16, v61, v45
	v_fmac_f32_e32 v16, v62, v46
	v_fmac_f32_e32 v16, v63, v47
	v_fmac_f32_e32 v16, v64, v48
	v_fmac_f32_e32 v16, v65, v49
	v_fmac_f32_e32 v16, v66, v50
	v_fmac_f32_e32 v16, v67, v51
	v_fmac_f32_e32 v16, v68, v52
	v_fmac_f32_e32 v16, v69, v53
	v_fmac_f32_e32 v16, v70, v54
	v_fmac_f32_e32 v16, v71, v55
	v_fmac_f32_e32 v16, v72, v56
	v_fmac_f32_e32 v16, v73, v57
	ds_read_b128 v[58:61], v20 offset:24576
	ds_read_b128 v[62:65], v20 offset:24592
	ds_read_b128 v[66:69], v20 offset:24608
	ds_read_b128 v[70:73], v20 offset:24624
	s_waitcnt lgkmcnt(4)
	v_fmac_f32_e32 v17, v74, v42
	v_fmac_f32_e32 v17, v75, v43
	v_fmac_f32_e32 v17, v76, v44
	v_fmac_f32_e32 v17, v77, v45
	v_fmac_f32_e32 v17, v78, v46
	v_fmac_f32_e32 v17, v79, v47
	v_fmac_f32_e32 v17, v80, v48
	v_fmac_f32_e32 v17, v81, v49
	v_fmac_f32_e32 v17, v82, v50
	v_fmac_f32_e32 v17, v83, v51
	v_fmac_f32_e32 v17, v84, v52
	v_fmac_f32_e32 v17, v85, v53
	v_fmac_f32_e32 v17, v86, v54
	v_fmac_f32_e32 v17, v87, v55
	v_fmac_f32_e32 v17, v88, v56
	v_fmac_f32_e32 v17, v89, v57
	ds_read_b128 v[74:77], v20 offset:28672
	ds_read_b128 v[78:81], v20 offset:28688
	ds_read_b128 v[82:85], v20 offset:28704
	ds_read_b128 v[86:89], v20 offset:28720
	s_waitcnt lgkmcnt(4)
	v_fmac_f32_e32 v10, v58, v42
	v_fmac_f32_e32 v10, v59, v43
	v_fmac_f32_e32 v10, v60, v44
	v_fmac_f32_e32 v10, v61, v45
	v_fmac_f32_e32 v10, v62, v46
	v_fmac_f32_e32 v10, v63, v47
	v_fmac_f32_e32 v10, v64, v48
	v_fmac_f32_e32 v10, v65, v49
	v_fmac_f32_e32 v10, v66, v50
	v_fmac_f32_e32 v10, v67, v51
	v_fmac_f32_e32 v10, v68, v52
	v_fmac_f32_e32 v10, v69, v53
	v_fmac_f32_e32 v10, v70, v54
	v_fmac_f32_e32 v10, v71, v55
	v_fmac_f32_e32 v10, v72, v56
	v_fmac_f32_e32 v10, v73, v57
	s_waitcnt lgkmcnt(0)
	v_fmac_f32_e32 v11, v74, v42
	v_fmac_f32_e32 v11, v75, v43
	v_fmac_f32_e32 v11, v76, v44
	v_fmac_f32_e32 v11, v77, v45
	v_fmac_f32_e32 v11, v78, v46
	v_fmac_f32_e32 v11, v79, v47
	v_fmac_f32_e32 v11, v80, v48
	v_fmac_f32_e32 v11, v81, v49
	v_fmac_f32_e32 v11, v82, v50
	v_fmac_f32_e32 v11, v83, v51
	v_fmac_f32_e32 v11, v84, v52
	v_fmac_f32_e32 v11, v85, v53
	v_fmac_f32_e32 v11, v86, v54
	v_fmac_f32_e32 v11, v87, v55
	v_fmac_f32_e32 v11, v88, v56
	v_fmac_f32_e32 v11, v89, v57
	v_mov_b32_e32 v20, s33
	s_add_i32 s33, s33, 64
	ds_read_b128 v[58:61], v20 offset:0
	ds_read_b128 v[62:65], v20 offset:16
	ds_read_b128 v[66:69], v20 offset:32
	ds_read_b128 v[70:73], v20 offset:48
	global_load_dword v42, v[18:19], off
	v_lshl_add_u64 v[18:19], v[18:19], 0, s[34:35]
	global_load_dword v43, v[18:19], off
	v_lshl_add_u64 v[18:19], v[18:19], 0, s[34:35]
	global_load_dword v44, v[18:19], off
	v_lshl_add_u64 v[18:19], v[18:19], 0, s[34:35]
	global_load_dword v45, v[18:19], off
	v_lshl_add_u64 v[18:19], v[18:19], 0, s[34:35]
	global_load_dword v46, v[18:19], off
	v_lshl_add_u64 v[18:19], v[18:19], 0, s[34:35]
	global_load_dword v47, v[18:19], off
	v_lshl_add_u64 v[18:19], v[18:19], 0, s[34:35]
	global_load_dword v48, v[18:19], off
	v_lshl_add_u64 v[18:19], v[18:19], 0, s[34:35]
	global_load_dword v49, v[18:19], off
	v_lshl_add_u64 v[18:19], v[18:19], 0, s[34:35]
	global_load_dword v50, v[18:19], off
	v_lshl_add_u64 v[18:19], v[18:19], 0, s[34:35]
	global_load_dword v51, v[18:19], off
	v_lshl_add_u64 v[18:19], v[18:19], 0, s[34:35]
	global_load_dword v52, v[18:19], off
	v_lshl_add_u64 v[18:19], v[18:19], 0, s[34:35]
	global_load_dword v53, v[18:19], off
	v_lshl_add_u64 v[18:19], v[18:19], 0, s[34:35]
	global_load_dword v54, v[18:19], off
	v_lshl_add_u64 v[18:19], v[18:19], 0, s[34:35]
	global_load_dword v55, v[18:19], off
	v_lshl_add_u64 v[18:19], v[18:19], 0, s[34:35]
	global_load_dword v56, v[18:19], off
	v_lshl_add_u64 v[18:19], v[18:19], 0, s[34:35]
	global_load_dword v57, v[18:19], off
	v_lshl_add_u64 v[18:19], v[18:19], 0, s[34:35]
	s_waitcnt vmcnt(16)
	ds_read_b128 v[74:77], v20 offset:4096
	ds_read_b128 v[78:81], v20 offset:4112
	ds_read_b128 v[82:85], v20 offset:4128
	ds_read_b128 v[86:89], v20 offset:4144
	s_waitcnt lgkmcnt(4)
	v_fmac_f32_e32 v12, v58, v26
	v_fmac_f32_e32 v12, v59, v27
	v_fmac_f32_e32 v12, v60, v28
	v_fmac_f32_e32 v12, v61, v29
	v_fmac_f32_e32 v12, v62, v30
	v_fmac_f32_e32 v12, v63, v31
	v_fmac_f32_e32 v12, v64, v32
	v_fmac_f32_e32 v12, v65, v33
	v_fmac_f32_e32 v12, v66, v34
	v_fmac_f32_e32 v12, v67, v35
	v_fmac_f32_e32 v12, v68, v36
	v_fmac_f32_e32 v12, v69, v37
	v_fmac_f32_e32 v12, v70, v38
	v_fmac_f32_e32 v12, v71, v39
	v_fmac_f32_e32 v12, v72, v40
	v_fmac_f32_e32 v12, v73, v41
	ds_read_b128 v[58:61], v20 offset:8192
	ds_read_b128 v[62:65], v20 offset:8208
	ds_read_b128 v[66:69], v20 offset:8224
	ds_read_b128 v[70:73], v20 offset:8240
	s_waitcnt lgkmcnt(4)
	v_fmac_f32_e32 v13, v74, v26
	v_fmac_f32_e32 v13, v75, v27
	v_fmac_f32_e32 v13, v76, v28
	v_fmac_f32_e32 v13, v77, v29
	v_fmac_f32_e32 v13, v78, v30
	v_fmac_f32_e32 v13, v79, v31
	v_fmac_f32_e32 v13, v80, v32
	v_fmac_f32_e32 v13, v81, v33
	v_fmac_f32_e32 v13, v82, v34
	v_fmac_f32_e32 v13, v83, v35
	v_fmac_f32_e32 v13, v84, v36
	v_fmac_f32_e32 v13, v85, v37
	v_fmac_f32_e32 v13, v86, v38
	v_fmac_f32_e32 v13, v87, v39
	v_fmac_f32_e32 v13, v88, v40
	v_fmac_f32_e32 v13, v89, v41
	ds_read_b128 v[74:77], v20 offset:12288
	ds_read_b128 v[78:81], v20 offset:12304
	ds_read_b128 v[82:85], v20 offset:12320
	ds_read_b128 v[86:89], v20 offset:12336
	s_waitcnt lgkmcnt(4)
	v_fmac_f32_e32 v14, v58, v26
	v_fmac_f32_e32 v14, v59, v27
	v_fmac_f32_e32 v14, v60, v28
	v_fmac_f32_e32 v14, v61, v29
	v_fmac_f32_e32 v14, v62, v30
	v_fmac_f32_e32 v14, v63, v31
	v_fmac_f32_e32 v14, v64, v32
	v_fmac_f32_e32 v14, v65, v33
	v_fmac_f32_e32 v14, v66, v34
	v_fmac_f32_e32 v14, v67, v35
	v_fmac_f32_e32 v14, v68, v36
	v_fmac_f32_e32 v14, v69, v37
	v_fmac_f32_e32 v14, v70, v38
	v_fmac_f32_e32 v14, v71, v39
	v_fmac_f32_e32 v14, v72, v40
	v_fmac_f32_e32 v14, v73, v41
	ds_read_b128 v[58:61], v20 offset:16384
	ds_read_b128 v[62:65], v20 offset:16400
	ds_read_b128 v[66:69], v20 offset:16416
	ds_read_b128 v[70:73], v20 offset:16432
	s_waitcnt lgkmcnt(4)
	v_fmac_f32_e32 v15, v74, v26
	v_fmac_f32_e32 v15, v75, v27
	v_fmac_f32_e32 v15, v76, v28
	v_fmac_f32_e32 v15, v77, v29
	v_fmac_f32_e32 v15, v78, v30
	v_fmac_f32_e32 v15, v79, v31
	v_fmac_f32_e32 v15, v80, v32
	v_fmac_f32_e32 v15, v81, v33
	v_fmac_f32_e32 v15, v82, v34
	v_fmac_f32_e32 v15, v83, v35
	v_fmac_f32_e32 v15, v84, v36
	v_fmac_f32_e32 v15, v85, v37
	v_fmac_f32_e32 v15, v86, v38
	v_fmac_f32_e32 v15, v87, v39
	v_fmac_f32_e32 v15, v88, v40
	v_fmac_f32_e32 v15, v89, v41
	ds_read_b128 v[74:77], v20 offset:20480
	ds_read_b128 v[78:81], v20 offset:20496
	ds_read_b128 v[82:85], v20 offset:20512
	ds_read_b128 v[86:89], v20 offset:20528
	s_waitcnt lgkmcnt(4)
	v_fmac_f32_e32 v16, v58, v26
	v_fmac_f32_e32 v16, v59, v27
	v_fmac_f32_e32 v16, v60, v28
	v_fmac_f32_e32 v16, v61, v29
	v_fmac_f32_e32 v16, v62, v30
	v_fmac_f32_e32 v16, v63, v31
	v_fmac_f32_e32 v16, v64, v32
	v_fmac_f32_e32 v16, v65, v33
	v_fmac_f32_e32 v16, v66, v34
	v_fmac_f32_e32 v16, v67, v35
	v_fmac_f32_e32 v16, v68, v36
	v_fmac_f32_e32 v16, v69, v37
	v_fmac_f32_e32 v16, v70, v38
	v_fmac_f32_e32 v16, v71, v39
	v_fmac_f32_e32 v16, v72, v40
	v_fmac_f32_e32 v16, v73, v41
	ds_read_b128 v[58:61], v20 offset:24576
	ds_read_b128 v[62:65], v20 offset:24592
	ds_read_b128 v[66:69], v20 offset:24608
	ds_read_b128 v[70:73], v20 offset:24624
	s_waitcnt lgkmcnt(4)
	v_fmac_f32_e32 v17, v74, v26
	v_fmac_f32_e32 v17, v75, v27
	v_fmac_f32_e32 v17, v76, v28
	v_fmac_f32_e32 v17, v77, v29
	v_fmac_f32_e32 v17, v78, v30
	v_fmac_f32_e32 v17, v79, v31
	v_fmac_f32_e32 v17, v80, v32
	v_fmac_f32_e32 v17, v81, v33
	v_fmac_f32_e32 v17, v82, v34
	v_fmac_f32_e32 v17, v83, v35
	v_fmac_f32_e32 v17, v84, v36
	v_fmac_f32_e32 v17, v85, v37
	v_fmac_f32_e32 v17, v86, v38
	v_fmac_f32_e32 v17, v87, v39
	v_fmac_f32_e32 v17, v88, v40
	v_fmac_f32_e32 v17, v89, v41
	ds_read_b128 v[74:77], v20 offset:28672
	ds_read_b128 v[78:81], v20 offset:28688
	ds_read_b128 v[82:85], v20 offset:28704
	ds_read_b128 v[86:89], v20 offset:28720
	s_waitcnt lgkmcnt(4)
	v_fmac_f32_e32 v10, v58, v26
	v_fmac_f32_e32 v10, v59, v27
	v_fmac_f32_e32 v10, v60, v28
	v_fmac_f32_e32 v10, v61, v29
	v_fmac_f32_e32 v10, v62, v30
	v_fmac_f32_e32 v10, v63, v31
	v_fmac_f32_e32 v10, v64, v32
	v_fmac_f32_e32 v10, v65, v33
	v_fmac_f32_e32 v10, v66, v34
	v_fmac_f32_e32 v10, v67, v35
	v_fmac_f32_e32 v10, v68, v36
	v_fmac_f32_e32 v10, v69, v37
	v_fmac_f32_e32 v10, v70, v38
	v_fmac_f32_e32 v10, v71, v39
	v_fmac_f32_e32 v10, v72, v40
	v_fmac_f32_e32 v10, v73, v41
	s_waitcnt lgkmcnt(0)
	v_fmac_f32_e32 v11, v74, v26
	v_fmac_f32_e32 v11, v75, v27
	v_fmac_f32_e32 v11, v76, v28
	v_fmac_f32_e32 v11, v77, v29
	v_fmac_f32_e32 v11, v78, v30
	v_fmac_f32_e32 v11, v79, v31
	v_fmac_f32_e32 v11, v80, v32
	v_fmac_f32_e32 v11, v81, v33
	v_fmac_f32_e32 v11, v82, v34
	v_fmac_f32_e32 v11, v83, v35
	v_fmac_f32_e32 v11, v84, v36
	v_fmac_f32_e32 v11, v85, v37
	v_fmac_f32_e32 v11, v86, v38
	v_fmac_f32_e32 v11, v87, v39
	v_fmac_f32_e32 v11, v88, v40
	v_fmac_f32_e32 v11, v89, v41
	v_mov_b32_e32 v20, s33
	s_add_i32 s33, s33, 64
	ds_read_b128 v[58:61], v20 offset:0
	ds_read_b128 v[62:65], v20 offset:16
	ds_read_b128 v[66:69], v20 offset:32
	ds_read_b128 v[70:73], v20 offset:48
	s_waitcnt vmcnt(0)
	ds_read_b128 v[74:77], v20 offset:4096
	ds_read_b128 v[78:81], v20 offset:4112
	ds_read_b128 v[82:85], v20 offset:4128
	ds_read_b128 v[86:89], v20 offset:4144
	s_waitcnt lgkmcnt(4)
	v_fmac_f32_e32 v12, v58, v42
	v_fmac_f32_e32 v12, v59, v43
	v_fmac_f32_e32 v12, v60, v44
	v_fmac_f32_e32 v12, v61, v45
	v_fmac_f32_e32 v12, v62, v46
	v_fmac_f32_e32 v12, v63, v47
	v_fmac_f32_e32 v12, v64, v48
	v_fmac_f32_e32 v12, v65, v49
	v_fmac_f32_e32 v12, v66, v50
	v_fmac_f32_e32 v12, v67, v51
	v_fmac_f32_e32 v12, v68, v52
	v_fmac_f32_e32 v12, v69, v53
	v_fmac_f32_e32 v12, v70, v54
	v_fmac_f32_e32 v12, v71, v55
	v_fmac_f32_e32 v12, v72, v56
	v_fmac_f32_e32 v12, v73, v57
	ds_read_b128 v[58:61], v20 offset:8192
	ds_read_b128 v[62:65], v20 offset:8208
	ds_read_b128 v[66:69], v20 offset:8224
	ds_read_b128 v[70:73], v20 offset:8240
	s_waitcnt lgkmcnt(4)
	v_fmac_f32_e32 v13, v74, v42
	v_fmac_f32_e32 v13, v75, v43
	v_fmac_f32_e32 v13, v76, v44
	v_fmac_f32_e32 v13, v77, v45
	v_fmac_f32_e32 v13, v78, v46
	v_fmac_f32_e32 v13, v79, v47
	v_fmac_f32_e32 v13, v80, v48
	v_fmac_f32_e32 v13, v81, v49
	v_fmac_f32_e32 v13, v82, v50
	v_fmac_f32_e32 v13, v83, v51
	v_fmac_f32_e32 v13, v84, v52
	v_fmac_f32_e32 v13, v85, v53
	v_fmac_f32_e32 v13, v86, v54
	v_fmac_f32_e32 v13, v87, v55
	v_fmac_f32_e32 v13, v88, v56
	v_fmac_f32_e32 v13, v89, v57
	ds_read_b128 v[74:77], v20 offset:12288
	ds_read_b128 v[78:81], v20 offset:12304
	ds_read_b128 v[82:85], v20 offset:12320
	ds_read_b128 v[86:89], v20 offset:12336
	s_waitcnt lgkmcnt(4)
	v_fmac_f32_e32 v14, v58, v42
	v_fmac_f32_e32 v14, v59, v43
	v_fmac_f32_e32 v14, v60, v44
	v_fmac_f32_e32 v14, v61, v45
	v_fmac_f32_e32 v14, v62, v46
	v_fmac_f32_e32 v14, v63, v47
	v_fmac_f32_e32 v14, v64, v48
	v_fmac_f32_e32 v14, v65, v49
	v_fmac_f32_e32 v14, v66, v50
	v_fmac_f32_e32 v14, v67, v51
	v_fmac_f32_e32 v14, v68, v52
	v_fmac_f32_e32 v14, v69, v53
	v_fmac_f32_e32 v14, v70, v54
	v_fmac_f32_e32 v14, v71, v55
	v_fmac_f32_e32 v14, v72, v56
	v_fmac_f32_e32 v14, v73, v57
	ds_read_b128 v[58:61], v20 offset:16384
	ds_read_b128 v[62:65], v20 offset:16400
	ds_read_b128 v[66:69], v20 offset:16416
	ds_read_b128 v[70:73], v20 offset:16432
	s_waitcnt lgkmcnt(4)
	v_fmac_f32_e32 v15, v74, v42
	v_fmac_f32_e32 v15, v75, v43
	v_fmac_f32_e32 v15, v76, v44
	v_fmac_f32_e32 v15, v77, v45
	v_fmac_f32_e32 v15, v78, v46
	v_fmac_f32_e32 v15, v79, v47
	v_fmac_f32_e32 v15, v80, v48
	v_fmac_f32_e32 v15, v81, v49
	v_fmac_f32_e32 v15, v82, v50
	v_fmac_f32_e32 v15, v83, v51
	v_fmac_f32_e32 v15, v84, v52
	v_fmac_f32_e32 v15, v85, v53
	v_fmac_f32_e32 v15, v86, v54
	v_fmac_f32_e32 v15, v87, v55
	v_fmac_f32_e32 v15, v88, v56
	v_fmac_f32_e32 v15, v89, v57
	ds_read_b128 v[74:77], v20 offset:20480
	ds_read_b128 v[78:81], v20 offset:20496
	ds_read_b128 v[82:85], v20 offset:20512
	ds_read_b128 v[86:89], v20 offset:20528
	s_waitcnt lgkmcnt(4)
	v_fmac_f32_e32 v16, v58, v42
	v_fmac_f32_e32 v16, v59, v43
	v_fmac_f32_e32 v16, v60, v44
	v_fmac_f32_e32 v16, v61, v45
	v_fmac_f32_e32 v16, v62, v46
	v_fmac_f32_e32 v16, v63, v47
	v_fmac_f32_e32 v16, v64, v48
	v_fmac_f32_e32 v16, v65, v49
	v_fmac_f32_e32 v16, v66, v50
	v_fmac_f32_e32 v16, v67, v51
	v_fmac_f32_e32 v16, v68, v52
	v_fmac_f32_e32 v16, v69, v53
	v_fmac_f32_e32 v16, v70, v54
	v_fmac_f32_e32 v16, v71, v55
	v_fmac_f32_e32 v16, v72, v56
	v_fmac_f32_e32 v16, v73, v57
	ds_read_b128 v[58:61], v20 offset:24576
	ds_read_b128 v[62:65], v20 offset:24592
	ds_read_b128 v[66:69], v20 offset:24608
	ds_read_b128 v[70:73], v20 offset:24624
	s_waitcnt lgkmcnt(4)
	v_fmac_f32_e32 v17, v74, v42
	v_fmac_f32_e32 v17, v75, v43
	v_fmac_f32_e32 v17, v76, v44
	v_fmac_f32_e32 v17, v77, v45
	v_fmac_f32_e32 v17, v78, v46
	v_fmac_f32_e32 v17, v79, v47
	v_fmac_f32_e32 v17, v80, v48
	v_fmac_f32_e32 v17, v81, v49
	v_fmac_f32_e32 v17, v82, v50
	v_fmac_f32_e32 v17, v83, v51
	v_fmac_f32_e32 v17, v84, v52
	v_fmac_f32_e32 v17, v85, v53
	v_fmac_f32_e32 v17, v86, v54
	v_fmac_f32_e32 v17, v87, v55
	v_fmac_f32_e32 v17, v88, v56
	v_fmac_f32_e32 v17, v89, v57
	ds_read_b128 v[74:77], v20 offset:28672
	ds_read_b128 v[78:81], v20 offset:28688
	ds_read_b128 v[82:85], v20 offset:28704
	ds_read_b128 v[86:89], v20 offset:28720
	s_waitcnt lgkmcnt(4)
	v_fmac_f32_e32 v10, v58, v42
	v_fmac_f32_e32 v10, v59, v43
	v_fmac_f32_e32 v10, v60, v44
	v_fmac_f32_e32 v10, v61, v45
	v_fmac_f32_e32 v10, v62, v46
	v_fmac_f32_e32 v10, v63, v47
	v_fmac_f32_e32 v10, v64, v48
	v_fmac_f32_e32 v10, v65, v49
	v_fmac_f32_e32 v10, v66, v50
	v_fmac_f32_e32 v10, v67, v51
	v_fmac_f32_e32 v10, v68, v52
	v_fmac_f32_e32 v10, v69, v53
	v_fmac_f32_e32 v10, v70, v54
	v_fmac_f32_e32 v10, v71, v55
	v_fmac_f32_e32 v10, v72, v56
	v_fmac_f32_e32 v10, v73, v57
	s_waitcnt lgkmcnt(0)
	v_fmac_f32_e32 v11, v74, v42
	v_fmac_f32_e32 v11, v75, v43
	v_fmac_f32_e32 v11, v76, v44
	v_fmac_f32_e32 v11, v77, v45
	v_fmac_f32_e32 v11, v78, v46
	v_fmac_f32_e32 v11, v79, v47
	v_fmac_f32_e32 v11, v80, v48
	v_fmac_f32_e32 v11, v81, v49
	v_fmac_f32_e32 v11, v82, v50
	v_fmac_f32_e32 v11, v83, v51
	v_fmac_f32_e32 v11, v84, v52
	v_fmac_f32_e32 v11, v85, v53
	v_fmac_f32_e32 v11, v86, v54
	v_fmac_f32_e32 v11, v87, v55
	v_fmac_f32_e32 v11, v88, v56
	v_fmac_f32_e32 v11, v89, v57
	s_load_dwordx16 s[36:51], s[0:1], 0x40
	v_or_b32_e32 v8, s10, v0
	v_ashrrev_i32_e32 v9, 31, v8
	v_add_u32_e32 v2, s14, v1
	ds_write2st64_b32 v2, v12, v13 offset0:128 offset1:129
	ds_write2st64_b32 v2, v14, v15 offset0:130 offset1:131
	ds_write2st64_b32 v2, v16, v17 offset0:132 offset1:133
	ds_write2st64_b32 v2, v10, v11 offset0:134 offset1:135
	s_waitcnt lgkmcnt(0)
	v_lshl_add_u64 v[8:9], v[8:9], 2, s[40:41]
	s_barrier
	global_load_dword v2, v[8:9], off
	ds_read2st64_b32 v[10:11], v24 offset0:128 offset1:136
	ds_read2st64_b32 v[12:13], v24 offset0:144 offset1:152
	ds_read2st64_b32 v[14:15], v24 offset0:160 offset1:168
	ds_read2st64_b32 v[16:17], v24 offset0:176 offset1:184
	v_lshl_add_u32 v18, s31, 3, v23
	v_mov_b64_e32 v[8:9], s[52:53]
	v_mad_i64_i32 v[8:9], s[6:7], v18, s2, v[8:9]
	v_mov_b32_e32 v7, v3
	s_add_i32 s30, s30, s15
	v_lshl_add_u64 v[8:9], s[10:11], 2, v[8:9]
	s_cmpk_gt_i32 s30, 0x11f
	v_lshl_add_u64 v[8:9], v[8:9], 0, v[6:7]
	s_waitcnt vmcnt(0) lgkmcnt(3)
	v_add_f32_e32 v2, v2, v10
	v_add_f32_e32 v2, v2, v11
	s_waitcnt lgkmcnt(2)
	v_add_f32_e32 v2, v2, v12
	v_add_f32_e32 v2, v2, v13
	s_waitcnt lgkmcnt(1)
	v_add_f32_e32 v2, v2, v14
	v_add_f32_e32 v2, v2, v15
	s_waitcnt lgkmcnt(0)
	v_add_f32_e32 v2, v2, v16
	v_add_f32_e32 v2, v2, v17
	global_store_dword v[8:9], v2, off
	s_barrier
	s_cbranch_scc0 .LBB0_18
